# attention epilogue: LDS merge reads hoisted 8 slots ahead with renamed registers (rescheduler)
# baseline (speedup 1.0000x reference)
.LBB0_1062:
	s_or_b64 exec, exec, s[22:23]
	s_waitcnt lgkmcnt(0)
	s_barrier
	s_and_saveexec_b64 s[0:1], vcc
	s_cbranch_execz .LBB0_1035
	s_lshl_b32 s4, s41, 9
	ds_read2st64_b32 v[94:95], v83 offset1:1
	ds_read2st64_b32 v[96:97], v82 offset1:1
	ds_read2st64_b32 v[98:99], v82 offset0:2 offset1:3
	ds_read2st64_b32 v[100:101], v82 offset0:4 offset1:5
	ds_read2st64_b32 v[102:103], v82 offset0:6 offset1:7
	ds_read2st64_b32 v[104:105], v83 offset0:2 offset1:3
	ds_read2st64_b32 v[106:107], v82 offset0:8 offset1:9
	ds_read2st64_b32 v[108:109], v82 offset0:10 offset1:11
	s_and_b32 s4, s4, 0x7000
	s_add_i32 s4, s4, s55
	v_readlane_b32 s68, v240, 1
	v_lshl_add_u64 v[64:65], v[164:165], 0, s[4:5]
	v_readlane_b32 s74, v240, 7
	v_readlane_b32 s75, v240, 8
	v_or_b32_e32 v64, v64, v159
	s_lshl_b32 s4, s41, 7
	v_mov_b64_e32 v[66:67], s[74:75]
	v_mad_u64_u32 v[68:69], s[22:23], v64, s39, v[66:67]
	v_mad_i32_i24 v69, v65, s39, v69
	s_and_b32 s4, s4, 0x380
	v_lshl_add_u64 v[68:69], v[68:69], 0, s[4:5]
	v_mov_b32_e32 v159, v157
	v_lshl_add_u64 v[68:69], v[68:69], 0, v[158:159]
	global_load_dwordx2 v[176:177], v[68:69], off
	global_load_dwordx2 v[178:179], v[68:69], off offset:16
	global_load_dwordx2 v[180:181], v[68:69], off offset:32
	global_load_dwordx2 v[182:183], v[68:69], off offset:48
	global_load_dwordx2 v[184:185], v[68:69], off offset:64
	global_load_dwordx2 v[186:187], v[68:69], off offset:80
	global_load_dwordx2 v[188:189], v[68:69], off offset:96
	global_load_dwordx2 v[190:191], v[68:69], off offset:112
	s_mov_b32 s98, 0x30000
	s_mov_b32 s99, 0
	v_lshl_add_u64 v[208:209], v[68:69], 0, s[98:99]
	global_load_dwordx2 v[192:193], v[208:209], off
	global_load_dwordx2 v[194:195], v[208:209], off offset:16
	global_load_dwordx2 v[196:197], v[208:209], off offset:32
	global_load_dwordx2 v[198:199], v[208:209], off offset:48
	global_load_dwordx2 v[200:201], v[208:209], off offset:64
	global_load_dwordx2 v[202:203], v[208:209], off offset:80
	global_load_dwordx2 v[204:205], v[208:209], off offset:96
	global_load_dwordx2 v[206:207], v[208:209], off offset:112
	ds_read2st64_b32 v[110:111], v82 offset0:12 offset1:13
	v_max_f32_e32 v86, v161, v161
	ds_read2st64_b32 v[112:113], v82 offset0:14 offset1:15
	ds_read2st64_b32 v[114:115], v82 offset0:16 offset1:17
	ds_read2st64_b32 v[116:117], v82 offset0:18 offset1:19
	ds_read2st64_b32 v[118:119], v82 offset0:20 offset1:21
	ds_read2st64_b32 v[120:121], v82 offset0:22 offset1:23
	v_readlane_b32 s76, v240, 9
	v_readlane_b32 s77, v240, 10
	s_waitcnt lgkmcnt(13)
	v_max_f32_e32 v83, v94, v94
	v_mov_b32_e32 v163, v95
	v_max_f32_e32 v79, v86, v83
	v_sub_f32_e32 v83, v161, v79
	v_sub_f32_e32 v79, v94, v79
	v_exp_f32_e32 v78, v83
	v_exp_f32_e32 v79, v79
	v_readlane_b32 s78, v240, 11
	v_readlane_b32 s79, v240, 12
	v_readlane_b32 s80, v240, 13
	v_pk_mul_f32 v[88:89], v[162:163], v[78:79]
	v_readlane_b32 s81, v240, 14
	v_add_f32_e32 v83, v88, v89
	v_div_scale_f32 v88, s[22:23], v83, v83, 1.0
	v_rcp_f32_e32 v89, v88
	v_div_scale_f32 v90, vcc, 1.0, v83, 1.0
	v_readlane_b32 s82, v240, 15
	v_fma_f32 v91, -v88, v89, 1.0
	v_fmac_f32_e32 v89, v91, v89
	v_mul_f32_e32 v91, v90, v89
	v_fma_f32 v92, -v88, v91, v90
	v_fmac_f32_e32 v91, v92, v89
	v_fma_f32 v88, -v88, v91, v90
	v_div_fmas_f32 v88, v88, v89, v91
	v_div_fixup_f32 v83, v88, v83, 1.0
	v_readlane_b32 s83, v240, 16
	s_mov_b64 s[44:45], s[76:77]
	v_mul_f32_e32 v88, v79, v83
	s_mov_b64 s[50:51], s[82:83]
	v_lshlrev_b64 v[86:87], 11, v[64:65]
	v_mul_f32_e32 v78, v78, v83
	s_waitcnt lgkmcnt(12)
	v_pk_mul_f32 v[72:73], v[96:97], v[88:89] op_sel_hi:[1,0]
	s_waitcnt lgkmcnt(11)
	v_pk_mul_f32 v[74:75], v[98:99], v[88:89] op_sel_hi:[1,0]
	v_lshl_add_u64 v[86:87], s[50:51], 0, v[86:87]
	v_pk_fma_f32 v[48:49], v[48:49], v[78:79], v[72:73] op_sel_hi:[1,0,1]
	v_pk_fma_f32 v[50:51], v[50:51], v[78:79], v[74:75] op_sel_hi:[1,0,1]
	v_lshl_add_u64 v[86:87], v[86:87], 0, s[4:5]
	v_lshl_add_u64 v[86:87], v[86:87], 0, v[158:159]
	v_or_b32_e32 v64, 32, v64
	s_waitcnt lgkmcnt(8)
	v_mov_b32_e32 v161, v105
	v_readlane_b32 s69, v240, 2
	v_readlane_b32 s70, v240, 3
	v_readlane_b32 s71, v240, 4
	v_readlane_b32 s72, v240, 5
	v_readlane_b32 s73, v240, 6
	s_mov_b64 s[46:47], s[78:79]
	s_mov_b64 s[48:49], s[80:81]
	s_waitcnt vmcnt(15)
	v_mov_b32_e32 v70, v176
	v_mov_b32_e32 v71, v177
	v_lshlrev_b32_e32 v72, 16, v70
	v_and_b32_e32 v73, 0xffff0000, v70
	v_lshlrev_b32_e32 v70, 16, v71
	v_and_b32_e32 v71, 0xffff0000, v71
	v_pk_mul_f32 v[48:49], v[48:49], v[72:73]
	v_pk_mul_f32 v[50:51], v[50:51], v[70:71]
	v_cvt_pk_bf16_f32 v48, v48, v49
	v_cvt_pk_bf16_f32 v49, v50, v51
	global_store_dwordx2 v[86:87], v[48:49], off
	v_pk_mul_f32 v[50:51], v[88:89], v[100:101] op_sel_hi:[0,1]
	v_pk_mul_f32 v[70:71], v[88:89], v[102:103] op_sel_hi:[0,1]
	v_pk_fma_f32 v[50:51], v[52:53], v[78:79], v[50:51] op_sel_hi:[1,0,1]
	v_pk_fma_f32 v[52:53], v[54:55], v[78:79], v[70:71] op_sel_hi:[1,0,1]
	s_waitcnt vmcnt(15)
	v_mov_b32_e32 v48, v178
	v_mov_b32_e32 v49, v179
	v_lshlrev_b32_e32 v54, 16, v48
	v_and_b32_e32 v55, 0xffff0000, v48
	v_lshlrev_b32_e32 v48, 16, v49
	v_and_b32_e32 v49, 0xffff0000, v49
	v_pk_mul_f32 v[50:51], v[50:51], v[54:55]
	v_pk_mul_f32 v[48:49], v[52:53], v[48:49]
	v_cvt_pk_bf16_f32 v50, v50, v51
	v_cvt_pk_bf16_f32 v51, v48, v49
	global_store_dwordx2 v[86:87], v[50:51], off offset:16
	ds_read2st64_b32 v[94:95], v82 offset0:24 offset1:25
	ds_read2st64_b32 v[96:97], v82 offset0:26 offset1:27
	ds_read2st64_b32 v[98:99], v82 offset0:28 offset1:29
	ds_read2st64_b32 v[100:101], v82 offset0:30 offset1:31
	s_waitcnt lgkmcnt(11)
	v_pk_mul_f32 v[50:51], v[88:89], v[106:107] op_sel_hi:[0,1]
	s_waitcnt lgkmcnt(10)
	v_pk_mul_f32 v[52:53], v[88:89], v[108:109] op_sel_hi:[0,1]
	v_pk_fma_f32 v[50:51], v[56:57], v[78:79], v[50:51] op_sel_hi:[1,0,1]
	v_pk_fma_f32 v[52:53], v[58:59], v[78:79], v[52:53] op_sel_hi:[1,0,1]
	s_waitcnt vmcnt(15)
	v_mov_b32_e32 v48, v180
	v_mov_b32_e32 v49, v181
	v_lshlrev_b32_e32 v56, 16, v48
	v_and_b32_e32 v57, 0xffff0000, v48
	v_lshlrev_b32_e32 v48, 16, v49
	v_and_b32_e32 v49, 0xffff0000, v49
	v_pk_mul_f32 v[50:51], v[50:51], v[56:57]
	v_pk_mul_f32 v[48:49], v[52:53], v[48:49]
	v_cvt_pk_bf16_f32 v50, v50, v51
	v_cvt_pk_bf16_f32 v51, v48, v49
	global_store_dwordx2 v[86:87], v[50:51], off offset:32
	s_waitcnt lgkmcnt(9)
	v_pk_mul_f32 v[50:51], v[88:89], v[110:111] op_sel_hi:[0,1]
	s_waitcnt lgkmcnt(8)
	v_pk_mul_f32 v[52:53], v[88:89], v[112:113] op_sel_hi:[0,1]
	v_pk_fma_f32 v[50:51], v[60:61], v[78:79], v[50:51] op_sel_hi:[1,0,1]
	v_pk_fma_f32 v[52:53], v[62:63], v[78:79], v[52:53] op_sel_hi:[1,0,1]
	s_waitcnt vmcnt(15)
	v_mov_b32_e32 v48, v182
	v_mov_b32_e32 v49, v183
	v_lshlrev_b32_e32 v54, 16, v48
	v_and_b32_e32 v55, 0xffff0000, v48
	v_lshlrev_b32_e32 v48, 16, v49
	v_and_b32_e32 v49, 0xffff0000, v49
	v_pk_mul_f32 v[50:51], v[50:51], v[54:55]
	v_pk_mul_f32 v[48:49], v[52:53], v[48:49]
	v_cvt_pk_bf16_f32 v50, v50, v51
	v_cvt_pk_bf16_f32 v51, v48, v49
	global_store_dwordx2 v[86:87], v[50:51], off offset:48
	ds_read2st64_b32 v[102:103], v82 offset0:32 offset1:33
	ds_read2st64_b32 v[106:107], v82 offset0:34 offset1:35
	ds_read2st64_b32 v[108:109], v82 offset0:36 offset1:37
	ds_read2st64_b32 v[110:111], v82 offset0:38 offset1:39
	s_waitcnt lgkmcnt(11)
	v_pk_mul_f32 v[50:51], v[88:89], v[114:115] op_sel_hi:[0,1]
	s_waitcnt lgkmcnt(10)
	v_pk_mul_f32 v[52:53], v[88:89], v[116:117] op_sel_hi:[0,1]
	v_pk_fma_f32 v[32:33], v[32:33], v[78:79], v[50:51] op_sel_hi:[1,0,1]
	v_pk_fma_f32 v[34:35], v[34:35], v[78:79], v[52:53] op_sel_hi:[1,0,1]
	s_waitcnt vmcnt(15)
	v_mov_b32_e32 v48, v184
	v_mov_b32_e32 v49, v185
	v_lshlrev_b32_e32 v50, 16, v48
	v_and_b32_e32 v51, 0xffff0000, v48
	v_lshlrev_b32_e32 v48, 16, v49
	v_and_b32_e32 v49, 0xffff0000, v49
	v_pk_mul_f32 v[32:33], v[32:33], v[50:51]
	v_pk_mul_f32 v[34:35], v[34:35], v[48:49]
	v_cvt_pk_bf16_f32 v32, v32, v33
	v_cvt_pk_bf16_f32 v33, v34, v35
	global_store_dwordx2 v[86:87], v[32:33], off offset:64
	s_waitcnt lgkmcnt(9)
	v_pk_mul_f32 v[34:35], v[88:89], v[118:119] op_sel_hi:[0,1]
	s_waitcnt lgkmcnt(8)
	v_pk_mul_f32 v[48:49], v[88:89], v[120:121] op_sel_hi:[0,1]
	v_pk_fma_f32 v[34:35], v[36:37], v[78:79], v[34:35] op_sel_hi:[1,0,1]
	v_pk_fma_f32 v[36:37], v[38:39], v[78:79], v[48:49] op_sel_hi:[1,0,1]
	s_waitcnt vmcnt(15)
	v_mov_b32_e32 v32, v186
	v_mov_b32_e32 v33, v187
	v_lshlrev_b32_e32 v38, 16, v32
	v_and_b32_e32 v39, 0xffff0000, v32
	v_lshlrev_b32_e32 v32, 16, v33
	v_and_b32_e32 v33, 0xffff0000, v33
	v_pk_mul_f32 v[34:35], v[34:35], v[38:39]
	v_pk_mul_f32 v[32:33], v[36:37], v[32:33]
	v_cvt_pk_bf16_f32 v34, v34, v35
	v_cvt_pk_bf16_f32 v35, v32, v33
	global_store_dwordx2 v[86:87], v[34:35], off offset:80
	ds_read2st64_b32 v[112:113], v82 offset0:40 offset1:41
	ds_read2st64_b32 v[114:115], v82 offset0:42 offset1:43
	ds_read2st64_b32 v[116:117], v82 offset0:44 offset1:45
	ds_read2st64_b32 v[118:119], v82 offset0:46 offset1:47
	s_waitcnt lgkmcnt(11)
	v_pk_mul_f32 v[34:35], v[88:89], v[94:95] op_sel_hi:[0,1]
	s_waitcnt lgkmcnt(10)
	v_pk_mul_f32 v[36:37], v[88:89], v[96:97] op_sel_hi:[0,1]
	v_pk_fma_f32 v[34:35], v[40:41], v[78:79], v[34:35] op_sel_hi:[1,0,1]
	v_pk_fma_f32 v[36:37], v[42:43], v[78:79], v[36:37] op_sel_hi:[1,0,1]
	s_waitcnt vmcnt(15)
	v_mov_b32_e32 v32, v188
	v_mov_b32_e32 v33, v189
	v_lshlrev_b32_e32 v40, 16, v32
	v_and_b32_e32 v41, 0xffff0000, v32
	v_lshlrev_b32_e32 v32, 16, v33
	v_and_b32_e32 v33, 0xffff0000, v33
	v_pk_mul_f32 v[34:35], v[34:35], v[40:41]
	v_pk_mul_f32 v[32:33], v[36:37], v[32:33]
	v_cvt_pk_bf16_f32 v34, v34, v35
	v_cvt_pk_bf16_f32 v35, v32, v33
	global_store_dwordx2 v[86:87], v[34:35], off offset:96
	s_waitcnt lgkmcnt(9)
	v_pk_mul_f32 v[36:37], v[88:89], v[98:99] op_sel_hi:[0,1]
	s_waitcnt lgkmcnt(8)
	v_pk_mul_f32 v[38:39], v[88:89], v[100:101] op_sel_hi:[0,1]
	v_mad_u64_u32 v[32:33], s[22:23], v64, s39, v[66:67]
	v_pk_fma_f32 v[36:37], v[44:45], v[78:79], v[36:37] op_sel_hi:[1,0,1]
	v_pk_fma_f32 v[38:39], v[46:47], v[78:79], v[38:39] op_sel_hi:[1,0,1]
	v_mad_i32_i24 v33, v65, s39, v33
	v_lshl_add_u64 v[32:33], v[32:33], 0, s[4:5]
	v_lshl_add_u64 v[32:33], v[32:33], 0, v[158:159]
	s_waitcnt vmcnt(15)
	v_mov_b32_e32 v34, v190
	v_mov_b32_e32 v35, v191
	v_lshlrev_b32_e32 v40, 16, v34
	v_and_b32_e32 v41, 0xffff0000, v34
	v_lshlrev_b32_e32 v34, 16, v35
	v_and_b32_e32 v35, 0xffff0000, v35
	v_pk_mul_f32 v[36:37], v[36:37], v[40:41]
	v_pk_mul_f32 v[34:35], v[38:39], v[34:35]
	v_cvt_pk_bf16_f32 v36, v36, v37
	v_cvt_pk_bf16_f32 v37, v34, v35
	global_store_dwordx2 v[86:87], v[36:37], off offset:112
	v_max_f32_e32 v34, v167, v167
	v_max_f32_e32 v35, v104, v104
	v_max_f32_e32 v34, v34, v35
	v_sub_f32_e32 v35, v167, v34
	v_sub_f32_e32 v34, v104, v34
	v_exp_f32_e32 v36, v35
	v_exp_f32_e32 v37, v34
	ds_read2st64_b32 v[94:95], v82 offset0:48 offset1:49
	ds_read2st64_b32 v[96:97], v82 offset0:50 offset1:51
	ds_read2st64_b32 v[98:99], v82 offset0:52 offset1:53
	ds_read2st64_b32 v[100:101], v82 offset0:54 offset1:55
	v_lshlrev_b64 v[34:35], 11, v[64:65]
	v_lshl_add_u64 v[34:35], s[50:51], 0, v[34:35]
	v_pk_mul_f32 v[38:39], v[160:161], v[36:37]
	v_lshl_add_u64 v[34:35], v[34:35], 0, s[4:5]
	v_add_f32_e32 v38, v38, v39
	v_div_scale_f32 v39, s[22:23], v38, v38, 1.0
	v_rcp_f32_e32 v50, v39
	v_div_scale_f32 v51, vcc, 1.0, v38, 1.0
	v_lshl_add_u64 v[34:35], v[34:35], 0, v[158:159]
	v_fma_f32 v52, -v39, v50, 1.0
	v_fmac_f32_e32 v50, v52, v50
	v_mul_f32_e32 v52, v51, v50
	v_fma_f32 v53, -v39, v52, v51
	v_fmac_f32_e32 v52, v53, v50
	v_fma_f32 v39, -v39, v52, v51
	v_div_fmas_f32 v39, v39, v50, v52
	v_div_fixup_f32 v38, v39, v38, 1.0
	v_mul_f32_e32 v36, v36, v38
	v_mul_f32_e32 v38, v37, v38
	s_waitcnt lgkmcnt(11)
	v_pk_mul_f32 v[42:43], v[102:103], v[38:39] op_sel_hi:[1,0]
	s_waitcnt lgkmcnt(10)
	v_pk_mul_f32 v[44:45], v[106:107], v[38:39] op_sel_hi:[1,0]
	v_pk_fma_f32 v[16:17], v[16:17], v[36:37], v[42:43] op_sel_hi:[1,0,1]
	v_pk_fma_f32 v[18:19], v[18:19], v[36:37], v[44:45] op_sel_hi:[1,0,1]
	s_waitcnt vmcnt(15)
	v_mov_b32_e32 v40, v192
	v_mov_b32_e32 v41, v193
	v_lshlrev_b32_e32 v42, 16, v40
	v_and_b32_e32 v43, 0xffff0000, v40
	v_lshlrev_b32_e32 v40, 16, v41
	v_and_b32_e32 v41, 0xffff0000, v41
	v_pk_mul_f32 v[16:17], v[16:17], v[42:43]
	v_pk_mul_f32 v[18:19], v[18:19], v[40:41]
	v_cvt_pk_bf16_f32 v16, v16, v17
	v_cvt_pk_bf16_f32 v17, v18, v19
	global_store_dwordx2 v[34:35], v[16:17], off
	s_waitcnt lgkmcnt(9)
	v_pk_mul_f32 v[18:19], v[38:39], v[108:109] op_sel_hi:[0,1]
	s_waitcnt lgkmcnt(8)
	v_pk_mul_f32 v[40:41], v[38:39], v[110:111] op_sel_hi:[0,1]
	v_pk_fma_f32 v[18:19], v[20:21], v[36:37], v[18:19] op_sel_hi:[1,0,1]
	v_pk_fma_f32 v[20:21], v[22:23], v[36:37], v[40:41] op_sel_hi:[1,0,1]
	s_waitcnt vmcnt(15)
	v_mov_b32_e32 v16, v194
	v_mov_b32_e32 v17, v195
	v_lshlrev_b32_e32 v22, 16, v16
	v_and_b32_e32 v23, 0xffff0000, v16
	v_lshlrev_b32_e32 v16, 16, v17
	v_and_b32_e32 v17, 0xffff0000, v17
	v_pk_mul_f32 v[18:19], v[18:19], v[22:23]
	v_pk_mul_f32 v[16:17], v[20:21], v[16:17]
	v_cvt_pk_bf16_f32 v18, v18, v19
	v_cvt_pk_bf16_f32 v19, v16, v17
	global_store_dwordx2 v[34:35], v[18:19], off offset:16
	ds_read2st64_b32 v[102:103], v82 offset0:56 offset1:57
	ds_read2st64_b32 v[104:105], v82 offset0:58 offset1:59
	ds_read2st64_b32 v[106:107], v82 offset0:60 offset1:61
	ds_read2st64_b32 v[108:109], v82 offset0:62 offset1:63
	s_waitcnt lgkmcnt(11)
	v_pk_mul_f32 v[18:19], v[38:39], v[112:113] op_sel_hi:[0,1]
	s_waitcnt lgkmcnt(10)
	v_pk_mul_f32 v[20:21], v[38:39], v[114:115] op_sel_hi:[0,1]
	v_pk_fma_f32 v[18:19], v[24:25], v[36:37], v[18:19] op_sel_hi:[1,0,1]
	v_pk_fma_f32 v[20:21], v[26:27], v[36:37], v[20:21] op_sel_hi:[1,0,1]
	s_waitcnt vmcnt(15)
	v_mov_b32_e32 v16, v196
	v_mov_b32_e32 v17, v197
	v_lshlrev_b32_e32 v24, 16, v16
	v_and_b32_e32 v25, 0xffff0000, v16
	v_lshlrev_b32_e32 v16, 16, v17
	v_and_b32_e32 v17, 0xffff0000, v17
	v_pk_mul_f32 v[18:19], v[18:19], v[24:25]
	v_pk_mul_f32 v[16:17], v[20:21], v[16:17]
	v_cvt_pk_bf16_f32 v18, v18, v19
	v_cvt_pk_bf16_f32 v19, v16, v17
	global_store_dwordx2 v[34:35], v[18:19], off offset:32
	s_waitcnt lgkmcnt(9)
	v_pk_mul_f32 v[18:19], v[38:39], v[116:117] op_sel_hi:[0,1]
	s_waitcnt lgkmcnt(8)
	v_pk_mul_f32 v[20:21], v[38:39], v[118:119] op_sel_hi:[0,1]
	v_pk_fma_f32 v[18:19], v[28:29], v[36:37], v[18:19] op_sel_hi:[1,0,1]
	v_pk_fma_f32 v[20:21], v[30:31], v[36:37], v[20:21] op_sel_hi:[1,0,1]
	s_waitcnt vmcnt(15)
	v_mov_b32_e32 v16, v198
	v_mov_b32_e32 v17, v199
	v_lshlrev_b32_e32 v22, 16, v16
	v_and_b32_e32 v23, 0xffff0000, v16
	v_lshlrev_b32_e32 v16, 16, v17
	v_and_b32_e32 v17, 0xffff0000, v17
	v_pk_mul_f32 v[18:19], v[18:19], v[22:23]
	v_pk_mul_f32 v[16:17], v[20:21], v[16:17]
	v_cvt_pk_bf16_f32 v18, v18, v19
	v_cvt_pk_bf16_f32 v19, v16, v17
	global_store_dwordx2 v[34:35], v[18:19], off offset:48
	s_waitcnt lgkmcnt(7)
	v_pk_mul_f32 v[18:19], v[38:39], v[94:95] op_sel_hi:[0,1]
	s_waitcnt lgkmcnt(6)
	v_pk_mul_f32 v[20:21], v[38:39], v[96:97] op_sel_hi:[0,1]
	v_pk_fma_f32 v[0:1], v[0:1], v[36:37], v[18:19] op_sel_hi:[1,0,1]
	v_pk_fma_f32 v[2:3], v[2:3], v[36:37], v[20:21] op_sel_hi:[1,0,1]
	s_waitcnt vmcnt(15)
	v_mov_b32_e32 v16, v200
	v_mov_b32_e32 v17, v201
	v_lshlrev_b32_e32 v18, 16, v16
	v_and_b32_e32 v19, 0xffff0000, v16
	v_lshlrev_b32_e32 v16, 16, v17
	v_and_b32_e32 v17, 0xffff0000, v17
	v_pk_mul_f32 v[0:1], v[0:1], v[18:19]
	v_pk_mul_f32 v[2:3], v[2:3], v[16:17]
	v_cvt_pk_bf16_f32 v0, v0, v1
	v_cvt_pk_bf16_f32 v1, v2, v3
	global_store_dwordx2 v[34:35], v[0:1], off offset:64
	s_waitcnt lgkmcnt(5)
	v_pk_mul_f32 v[2:3], v[38:39], v[98:99] op_sel_hi:[0,1]
	s_waitcnt lgkmcnt(4)
	v_pk_mul_f32 v[16:17], v[38:39], v[100:101] op_sel_hi:[0,1]
	v_pk_fma_f32 v[2:3], v[4:5], v[36:37], v[2:3] op_sel_hi:[1,0,1]
	v_pk_fma_f32 v[4:5], v[6:7], v[36:37], v[16:17] op_sel_hi:[1,0,1]
	s_waitcnt vmcnt(15)
	v_mov_b32_e32 v0, v202
	v_mov_b32_e32 v1, v203
	v_lshlrev_b32_e32 v6, 16, v0
	v_and_b32_e32 v7, 0xffff0000, v0
	v_lshlrev_b32_e32 v0, 16, v1
	v_and_b32_e32 v1, 0xffff0000, v1
	v_pk_mul_f32 v[2:3], v[2:3], v[6:7]
	v_pk_mul_f32 v[0:1], v[4:5], v[0:1]
	v_cvt_pk_bf16_f32 v2, v2, v3
	v_cvt_pk_bf16_f32 v3, v0, v1
	global_store_dwordx2 v[34:35], v[2:3], off offset:80
	s_waitcnt lgkmcnt(3)
	v_pk_mul_f32 v[2:3], v[38:39], v[102:103] op_sel_hi:[0,1]
	s_waitcnt lgkmcnt(2)
	v_pk_mul_f32 v[4:5], v[38:39], v[104:105] op_sel_hi:[0,1]
	v_pk_fma_f32 v[2:3], v[8:9], v[36:37], v[2:3] op_sel_hi:[1,0,1]
	v_pk_fma_f32 v[4:5], v[10:11], v[36:37], v[4:5] op_sel_hi:[1,0,1]
	s_waitcnt vmcnt(15)
	v_mov_b32_e32 v0, v204
	v_mov_b32_e32 v1, v205
	v_lshlrev_b32_e32 v8, 16, v0
	v_and_b32_e32 v9, 0xffff0000, v0
	v_lshlrev_b32_e32 v0, 16, v1
	v_and_b32_e32 v1, 0xffff0000, v1
	v_pk_mul_f32 v[2:3], v[2:3], v[8:9]
	v_pk_mul_f32 v[0:1], v[4:5], v[0:1]
	v_cvt_pk_bf16_f32 v2, v2, v3
	v_cvt_pk_bf16_f32 v3, v0, v1
	global_store_dwordx2 v[34:35], v[2:3], off offset:96
	s_waitcnt lgkmcnt(1)
	v_pk_mul_f32 v[2:3], v[38:39], v[106:107] op_sel_hi:[0,1]
	s_waitcnt lgkmcnt(0)
	v_pk_mul_f32 v[4:5], v[38:39], v[108:109] op_sel_hi:[0,1]
	v_pk_fma_f32 v[2:3], v[12:13], v[36:37], v[2:3] op_sel_hi:[1,0,1]
	v_pk_fma_f32 v[4:5], v[14:15], v[36:37], v[4:5] op_sel_hi:[1,0,1]
	s_waitcnt vmcnt(15)
	v_mov_b32_e32 v0, v206
	v_mov_b32_e32 v1, v207
	v_lshlrev_b32_e32 v6, 16, v0
	v_and_b32_e32 v7, 0xffff0000, v0
	v_lshlrev_b32_e32 v0, 16, v1
	v_and_b32_e32 v1, 0xffff0000, v1
	v_pk_mul_f32 v[2:3], v[2:3], v[6:7]
	v_pk_mul_f32 v[0:1], v[4:5], v[0:1]
	v_cvt_pk_bf16_f32 v2, v2, v3
	v_cvt_pk_bf16_f32 v3, v0, v1
	global_store_dwordx2 v[34:35], v[2:3], off offset:112
	s_branch .LBB0_1035
